# NSA item: extra workgroup barrier between the selected-block loop and the sliding-window loop (re-align the waves that stream the same K/V)
# speedup vs baseline: 1.0012x; 1.0012x over previous
.LBB0_819:
	s_barrier
	v_and_b32_e32 v64, 0xffff0000, v164
	v_mul_f32_e32 v64, 0xbfb8aa3b, v64
	v_exp_f32_e32 v64, v64
	v_lshlrev_b32_e32 v65, 16, v166
	v_mul_f32_e32 v65, 0xbfb8aa3b, v65
	v_exp_f32_e32 v65, v65
	v_add_f32_e32 v64, 1.0, v64
	v_div_scale_f32 v66, s[2:3], v64, v64, 1.0
	v_rcp_f32_e32 v67, v66
	v_div_scale_f32 v70, vcc, 1.0, v64, 1.0
	v_add_f32_e32 v65, 1.0, v65
	v_fma_f32 v68, -v66, v67, 1.0
	v_fmac_f32_e32 v67, v68, v67
	v_mul_f32_e32 v71, v70, v67
	v_fma_f32 v68, -v66, v71, v70
	v_fmac_f32_e32 v71, v68, v67
	global_load_dwordx2 v[68:69], v[160:161], off
	v_fma_f32 v66, -v66, v71, v70
	v_div_scale_f32 v70, s[2:3], v65, v65, 1.0
	v_rcp_f32_e32 v72, v70
	v_div_fmas_f32 v66, v66, v67, v71
	ds_bpermute_b32 v67, v177, v215
	v_div_fixup_f32 v64, v66, v64, 1.0
	v_fma_f32 v66, -v70, v72, 1.0
	v_fmac_f32_e32 v72, v66, v72
	v_div_scale_f32 v66, vcc, 1.0, v65, 1.0
	v_mul_f32_e32 v71, v66, v72
	v_fma_f32 v73, -v70, v71, v66
	v_fmac_f32_e32 v71, v73, v72
	s_waitcnt lgkmcnt(0)
	v_add_f32_e32 v73, v215, v67
	v_div_scale_f32 v74, s[2:3], v73, v73, 1.0
	v_rcp_f32_e32 v75, v74
	v_fma_f32 v70, -v70, v71, v66
	v_div_fmas_f32 v70, v70, v72, v71
	v_div_fixup_f32 v65, v70, v65, 1.0
	v_fma_f32 v70, -v74, v75, 1.0
	v_fmac_f32_e32 v75, v70, v75
	v_div_scale_f32 v70, vcc, 1.0, v73, 1.0
	v_mul_f32_e32 v71, v70, v75
	v_fma_f32 v72, -v74, v71, v70
	v_fmac_f32_e32 v71, v72, v75
	ds_bpermute_b32 v72, v177, v214
	v_fma_f32 v70, -v74, v71, v70
	v_div_fmas_f32 v70, v70, v75, v71
	v_div_fixup_f32 v70, v70, v73, 1.0
	v_cmp_lt_f32_e32 vcc, 0, v73
	s_waitcnt lgkmcnt(0)
	v_add_f32_e32 v74, v214, v72
	v_div_scale_f32 v75, s[2:3], v74, v74, 1.0
	v_rcp_f32_e32 v76, v75
	v_cndmask_b32_e32 v72, 0, v70, vcc
	v_mul_f32_e32 v72, v64, v72
	global_load_dwordx2 v[66:67], v[160:161], off offset:64
	v_fma_f32 v64, -v75, v76, 1.0
	v_fmac_f32_e32 v76, v64, v76
	v_div_scale_f32 v64, vcc, 1.0, v74, 1.0
	v_mul_f32_e32 v73, v64, v76
	v_fma_f32 v77, -v75, v73, v64
	v_fmac_f32_e32 v73, v77, v76
	v_fma_f32 v64, -v75, v73, v64
	v_div_fmas_f32 v64, v64, v76, v73
	v_div_fixup_f32 v64, v64, v74, 1.0
	v_cmp_lt_f32_e32 vcc, 0, v74
	global_load_dwordx2 v[74:75], v[160:161], off offset:80
	global_load_dwordx2 v[70:71], v[160:161], off offset:16
	v_pk_mul_f32 v[62:63], v[62:63], v[72:73] op_sel_hi:[1,0]
	v_pk_mul_f32 v[60:61], v[60:61], v[72:73] op_sel_hi:[1,0]
	v_pk_mul_f32 v[58:59], v[58:59], v[72:73] op_sel_hi:[1,0]
	v_pk_mul_f32 v[56:57], v[56:57], v[72:73] op_sel_hi:[1,0]
	v_pk_mul_f32 v[54:55], v[54:55], v[72:73] op_sel_hi:[1,0]
	v_pk_mul_f32 v[52:53], v[52:53], v[72:73] op_sel_hi:[1,0]
	v_pk_mul_f32 v[50:51], v[50:51], v[72:73] op_sel_hi:[1,0]
	v_pk_mul_f32 v[76:77], v[48:49], v[72:73] op_sel_hi:[1,0]
	v_pk_mul_f32 v[48:49], v[44:45], v[72:73] op_sel_hi:[1,0]
	v_pk_mul_f32 v[44:45], v[46:47], v[72:73] op_sel_hi:[1,0]
	v_pk_mul_f32 v[46:47], v[40:41], v[72:73] op_sel_hi:[1,0]
	v_pk_mul_f32 v[40:41], v[42:43], v[72:73] op_sel_hi:[1,0]
	v_pk_mul_f32 v[36:37], v[36:37], v[72:73] op_sel_hi:[1,0]
	v_pk_mul_f32 v[38:39], v[38:39], v[72:73] op_sel_hi:[1,0]
	v_pk_mul_f32 v[32:33], v[32:33], v[72:73] op_sel_hi:[1,0]
	v_pk_mul_f32 v[34:35], v[34:35], v[72:73] op_sel_hi:[1,0]
	global_load_dwordx2 v[42:43], v[160:161], off offset:32
	global_load_dwordx2 v[72:73], v[160:161], off offset:48
	v_pk_mov_b32 v[80:81], v[76:77], v[50:51] op_sel:[1,0]
	v_mov_b32_e32 v77, v51
	v_cndmask_b32_e32 v64, 0, v64, vcc
	v_mul_f32_e32 v64, v65, v64
	s_max_i32 s2, s91, 0x200
	s_add_i32 s21, s2, 0xfffffe00
	v_mov_b32_e32 v163, 0
	s_lshr_b32 s3, s21, 5
	s_ashr_i32 s2, s91, 5
	s_waitcnt vmcnt(5)
	v_and_b32_e32 v78, 0xffff0000, v68
	v_lshlrev_b32_e32 v79, 16, v69
	v_lshlrev_b32_e32 v68, 16, v68
	v_and_b32_e32 v69, 0xffff0000, v69
	v_pk_add_f32 v[78:79], v[80:81], v[78:79]
	v_pk_add_f32 v[50:51], v[76:77], v[68:69]
	v_and_b32_sdwa v68, v78, v232 dst_sel:DWORD dst_unused:UNUSED_PAD src0_sel:WORD_1 src1_sel:DWORD
	v_add3_u32 v68, v78, v68, s81
	v_and_b32_sdwa v76, v50, v232 dst_sel:DWORD dst_unused:UNUSED_PAD src0_sel:WORD_1 src1_sel:DWORD
	v_and_b32_e32 v68, 0xffff0000, v68
	v_and_b32_sdwa v69, v51, v232 dst_sel:DWORD dst_unused:UNUSED_PAD src0_sel:WORD_1 src1_sel:DWORD
	v_add3_u32 v50, v50, v76, s81
	v_add3_u32 v51, v51, v69, s81
	v_or_b32_sdwa v50, v50, v68 dst_sel:DWORD dst_unused:UNUSED_PAD src0_sel:WORD_1 src1_sel:DWORD
	global_load_dwordx2 v[68:69], v[160:161], off offset:96
	global_load_dwordx2 v[76:77], v[160:161], off offset:112
	v_and_b32_sdwa v65, v79, v232 dst_sel:DWORD dst_unused:UNUSED_PAD src0_sel:WORD_1 src1_sel:DWORD
	v_add3_u32 v65, v79, v65, s81
	v_mov_b32_e32 v81, v34
	v_mov_b32_e32 v34, v33
	v_and_b32_e32 v51, 0xffff0000, v51
	v_mov_b32_e32 v80, v32
	v_or_b32_sdwa v51, v51, v65 dst_sel:DWORD dst_unused:UNUSED_PAD src0_sel:DWORD src1_sel:WORD_1
	s_cmp_gt_i32 s3, s2
	v_mov_b32_e32 v162, v163
	s_waitcnt vmcnt(6)
	v_lshlrev_b32_e32 v79, 16, v67
	v_lshlrev_b32_e32 v78, 16, v66
	v_and_b32_e32 v67, 0xffff0000, v67
	v_and_b32_e32 v66, 0xffff0000, v66
	v_pk_add_f32 v[32:33], v[34:35], v[66:67]
	v_pk_add_f32 v[78:79], v[80:81], v[78:79]
	v_and_b32_sdwa v65, v33, v232 dst_sel:DWORD dst_unused:UNUSED_PAD src0_sel:WORD_1 src1_sel:DWORD
	v_and_b32_sdwa v66, v32, v232 dst_sel:DWORD dst_unused:UNUSED_PAD src0_sel:WORD_1 src1_sel:DWORD
	v_and_b32_sdwa v34, v79, v232 dst_sel:DWORD dst_unused:UNUSED_PAD src0_sel:WORD_1 src1_sel:DWORD
	v_and_b32_sdwa v35, v78, v232 dst_sel:DWORD dst_unused:UNUSED_PAD src0_sel:WORD_1 src1_sel:DWORD
	v_add3_u32 v33, v33, v65, s81
	v_add3_u32 v32, v32, v66, s81
	v_add3_u32 v35, v78, v35, s81
	v_add3_u32 v34, v79, v34, s81
	v_and_b32_e32 v33, 0xffff0000, v33
	v_and_b32_e32 v32, 0xffff0000, v32
	v_or_b32_sdwa v33, v33, v34 dst_sel:DWORD dst_unused:UNUSED_PAD src0_sel:DWORD src1_sel:WORD_1
	v_or_b32_sdwa v32, v32, v35 dst_sel:DWORD dst_unused:UNUSED_PAD src0_sel:DWORD src1_sel:WORD_1
	global_store_dwordx2 v[160:161], v[50:51], off
	global_store_dwordx2 v[160:161], v[32:33], off offset:64
	s_waitcnt vmcnt(6)
	v_and_b32_e32 v32, 0xffff0000, v70
	v_lshlrev_b32_e32 v33, 16, v71
	v_pk_mov_b32 v[50:51], v[52:53], v[54:55] op_sel:[1,0]
	v_lshlrev_b32_e32 v34, 16, v70
	v_and_b32_e32 v35, 0xffff0000, v71
	v_pk_add_f32 v[32:33], v[50:51], v[32:33]
	v_mov_b32_e32 v53, v55
	v_pk_add_f32 v[34:35], v[52:53], v[34:35]
	v_and_b32_sdwa v50, v33, v232 dst_sel:DWORD dst_unused:UNUSED_PAD src0_sel:WORD_1 src1_sel:DWORD
	v_and_b32_sdwa v51, v32, v232 dst_sel:DWORD dst_unused:UNUSED_PAD src0_sel:WORD_1 src1_sel:DWORD
	v_add3_u32 v33, v33, v50, s81
	v_and_b32_sdwa v50, v35, v232 dst_sel:DWORD dst_unused:UNUSED_PAD src0_sel:WORD_1 src1_sel:DWORD
	v_add3_u32 v32, v32, v51, s81
	v_and_b32_sdwa v51, v34, v232 dst_sel:DWORD dst_unused:UNUSED_PAD src0_sel:WORD_1 src1_sel:DWORD
	v_add3_u32 v35, v35, v50, s81
	v_and_b32_e32 v32, 0xffff0000, v32
	v_add3_u32 v34, v34, v51, s81
	v_and_b32_e32 v35, 0xffff0000, v35
	v_or_b32_sdwa v33, v35, v33 dst_sel:DWORD dst_unused:UNUSED_PAD src0_sel:DWORD src1_sel:WORD_1
	v_or_b32_sdwa v32, v34, v32 dst_sel:DWORD dst_unused:UNUSED_PAD src0_sel:WORD_1 src1_sel:DWORD
	v_lshlrev_b32_e32 v35, 16, v75
	v_lshlrev_b32_e32 v34, 16, v74
	v_mov_b32_e32 v52, v36
	v_mov_b32_e32 v53, v38
	v_and_b32_e32 v51, 0xffff0000, v75
	v_and_b32_e32 v50, 0xffff0000, v74
	v_pk_add_f32 v[34:35], v[52:53], v[34:35]
	v_mov_b32_e32 v38, v37
	v_pk_add_f32 v[36:37], v[38:39], v[50:51]
	v_and_b32_sdwa v38, v35, v232 dst_sel:DWORD dst_unused:UNUSED_PAD src0_sel:WORD_1 src1_sel:DWORD
	v_and_b32_sdwa v39, v34, v232 dst_sel:DWORD dst_unused:UNUSED_PAD src0_sel:WORD_1 src1_sel:DWORD
	v_add3_u32 v34, v34, v39, s81
	v_add3_u32 v35, v35, v38, s81
	v_and_b32_sdwa v38, v37, v232 dst_sel:DWORD dst_unused:UNUSED_PAD src0_sel:WORD_1 src1_sel:DWORD
	v_and_b32_sdwa v39, v36, v232 dst_sel:DWORD dst_unused:UNUSED_PAD src0_sel:WORD_1 src1_sel:DWORD
	v_add3_u32 v37, v37, v38, s81
	v_add3_u32 v36, v36, v39, s81
	v_and_b32_e32 v37, 0xffff0000, v37
	v_and_b32_e32 v36, 0xffff0000, v36
	v_or_b32_sdwa v35, v37, v35 dst_sel:DWORD dst_unused:UNUSED_PAD src0_sel:DWORD src1_sel:WORD_1
	v_or_b32_sdwa v34, v36, v34 dst_sel:DWORD dst_unused:UNUSED_PAD src0_sel:DWORD src1_sel:WORD_1
	global_store_dwordx2 v[160:161], v[32:33], off offset:16
	global_store_dwordx2 v[160:161], v[34:35], off offset:80
	s_waitcnt vmcnt(7)
	v_and_b32_e32 v32, 0xffff0000, v42
	v_lshlrev_b32_e32 v33, 16, v43
	v_pk_mov_b32 v[36:37], v[56:57], v[58:59] op_sel:[1,0]
	v_lshlrev_b32_e32 v34, 16, v42
	v_and_b32_e32 v35, 0xffff0000, v43
	v_pk_add_f32 v[32:33], v[36:37], v[32:33]
	v_mov_b32_e32 v57, v59
	v_pk_add_f32 v[34:35], v[56:57], v[34:35]
	v_and_b32_sdwa v36, v33, v232 dst_sel:DWORD dst_unused:UNUSED_PAD src0_sel:WORD_1 src1_sel:DWORD
	v_and_b32_sdwa v37, v32, v232 dst_sel:DWORD dst_unused:UNUSED_PAD src0_sel:WORD_1 src1_sel:DWORD
	v_add3_u32 v33, v33, v36, s81
	v_and_b32_sdwa v36, v35, v232 dst_sel:DWORD dst_unused:UNUSED_PAD src0_sel:WORD_1 src1_sel:DWORD
	v_add3_u32 v32, v32, v37, s81
	v_and_b32_sdwa v37, v34, v232 dst_sel:DWORD dst_unused:UNUSED_PAD src0_sel:WORD_1 src1_sel:DWORD
	v_add3_u32 v35, v35, v36, s81
	v_and_b32_e32 v32, 0xffff0000, v32
	v_add3_u32 v34, v34, v37, s81
	v_and_b32_e32 v35, 0xffff0000, v35
	v_or_b32_sdwa v35, v35, v33 dst_sel:DWORD dst_unused:UNUSED_PAD src0_sel:DWORD src1_sel:WORD_1
	v_or_b32_sdwa v34, v34, v32 dst_sel:DWORD dst_unused:UNUSED_PAD src0_sel:WORD_1 src1_sel:DWORD
	s_waitcnt vmcnt(5)
	v_lshlrev_b32_e32 v33, 16, v69
	v_lshlrev_b32_e32 v32, 16, v68
	v_mov_b32_e32 v38, v46
	v_mov_b32_e32 v39, v40
	v_pk_add_f32 v[38:39], v[38:39], v[32:33]
	global_load_dwordx2 v[32:33], v[160:161], off offset:128
	v_and_b32_e32 v37, 0xffff0000, v69
	v_and_b32_e32 v36, 0xffff0000, v68
	v_mov_b32_e32 v40, v47
	v_pk_add_f32 v[36:37], v[40:41], v[36:37]
	v_and_b32_sdwa v40, v39, v232 dst_sel:DWORD dst_unused:UNUSED_PAD src0_sel:WORD_1 src1_sel:DWORD
	v_and_b32_sdwa v41, v38, v232 dst_sel:DWORD dst_unused:UNUSED_PAD src0_sel:WORD_1 src1_sel:DWORD
	v_add3_u32 v38, v38, v41, s81
	v_add3_u32 v39, v39, v40, s81
	v_and_b32_sdwa v40, v37, v232 dst_sel:DWORD dst_unused:UNUSED_PAD src0_sel:WORD_1 src1_sel:DWORD
	v_and_b32_sdwa v41, v36, v232 dst_sel:DWORD dst_unused:UNUSED_PAD src0_sel:WORD_1 src1_sel:DWORD
	v_add3_u32 v37, v37, v40, s81
	v_add3_u32 v36, v36, v41, s81
	v_and_b32_e32 v37, 0xffff0000, v37
	v_and_b32_e32 v36, 0xffff0000, v36
	v_or_b32_sdwa v37, v37, v39 dst_sel:DWORD dst_unused:UNUSED_PAD src0_sel:DWORD src1_sel:WORD_1
	v_or_b32_sdwa v36, v36, v38 dst_sel:DWORD dst_unused:UNUSED_PAD src0_sel:DWORD src1_sel:WORD_1
	global_store_dwordx2 v[160:161], v[34:35], off offset:32
	global_store_dwordx2 v[160:161], v[36:37], off offset:96
	v_and_b32_e32 v34, 0xffff0000, v72
	v_lshlrev_b32_e32 v35, 16, v73
	v_pk_mov_b32 v[38:39], v[60:61], v[62:63] op_sel:[1,0]
	v_lshlrev_b32_e32 v36, 16, v72
	v_and_b32_e32 v37, 0xffff0000, v73
	v_pk_add_f32 v[38:39], v[38:39], v[34:35]
	global_load_dwordx2 v[34:35], v[160:161], off offset:192
	v_mov_b32_e32 v61, v63
	v_pk_add_f32 v[36:37], v[60:61], v[36:37]
	v_and_b32_sdwa v40, v39, v232 dst_sel:DWORD dst_unused:UNUSED_PAD src0_sel:WORD_1 src1_sel:DWORD
	v_and_b32_sdwa v41, v38, v232 dst_sel:DWORD dst_unused:UNUSED_PAD src0_sel:WORD_1 src1_sel:DWORD
	v_add3_u32 v39, v39, v40, s81
	v_and_b32_sdwa v40, v37, v232 dst_sel:DWORD dst_unused:UNUSED_PAD src0_sel:WORD_1 src1_sel:DWORD
	v_add3_u32 v38, v38, v41, s81
	v_and_b32_sdwa v41, v36, v232 dst_sel:DWORD dst_unused:UNUSED_PAD src0_sel:WORD_1 src1_sel:DWORD
	v_add3_u32 v37, v37, v40, s81
	v_and_b32_e32 v38, 0xffff0000, v38
	v_add3_u32 v36, v36, v41, s81
	v_and_b32_e32 v37, 0xffff0000, v37
	v_or_b32_sdwa v37, v37, v39 dst_sel:DWORD dst_unused:UNUSED_PAD src0_sel:DWORD src1_sel:WORD_1
	v_or_b32_sdwa v36, v36, v38 dst_sel:DWORD dst_unused:UNUSED_PAD src0_sel:WORD_1 src1_sel:DWORD
	s_waitcnt vmcnt(8)
	v_lshlrev_b32_e32 v39, 16, v77
	v_lshlrev_b32_e32 v38, 16, v76
	v_mov_b32_e32 v42, v48
	v_mov_b32_e32 v43, v44
	v_and_b32_e32 v41, 0xffff0000, v77
	v_and_b32_e32 v40, 0xffff0000, v76
	v_pk_add_f32 v[38:39], v[42:43], v[38:39]
	v_mov_b32_e32 v44, v49
	global_load_dwordx2 v[42:43], v[160:161], off offset:144
	v_pk_add_f32 v[40:41], v[44:45], v[40:41]
	v_and_b32_sdwa v44, v39, v232 dst_sel:DWORD dst_unused:UNUSED_PAD src0_sel:WORD_1 src1_sel:DWORD
	v_and_b32_sdwa v45, v38, v232 dst_sel:DWORD dst_unused:UNUSED_PAD src0_sel:WORD_1 src1_sel:DWORD
	v_add3_u32 v38, v38, v45, s81
	v_add3_u32 v39, v39, v44, s81
	v_and_b32_sdwa v44, v41, v232 dst_sel:DWORD dst_unused:UNUSED_PAD src0_sel:WORD_1 src1_sel:DWORD
	v_and_b32_sdwa v45, v40, v232 dst_sel:DWORD dst_unused:UNUSED_PAD src0_sel:WORD_1 src1_sel:DWORD
	v_add3_u32 v41, v41, v44, s81
	v_add3_u32 v40, v40, v45, s81
	v_and_b32_e32 v41, 0xffff0000, v41
	v_and_b32_e32 v40, 0xffff0000, v40
	v_or_b32_sdwa v39, v41, v39 dst_sel:DWORD dst_unused:UNUSED_PAD src0_sel:DWORD src1_sel:WORD_1
	v_or_b32_sdwa v38, v40, v38 dst_sel:DWORD dst_unused:UNUSED_PAD src0_sel:DWORD src1_sel:WORD_1
	global_store_dwordx2 v[160:161], v[36:37], off offset:48
	global_store_dwordx2 v[160:161], v[38:39], off offset:112
	global_load_dwordx2 v[36:37], v[160:161], off offset:208
	v_pk_mul_f32 v[18:19], v[18:19], v[64:65] op_sel_hi:[1,0]
	v_pk_mul_f32 v[38:39], v[16:17], v[64:65] op_sel_hi:[1,0]
	v_pk_mul_f32 v[16:17], v[12:13], v[64:65] op_sel_hi:[1,0]
	v_pk_mul_f32 v[12:13], v[14:15], v[64:65] op_sel_hi:[1,0]
	global_load_dwordx2 v[14:15], v[160:161], off offset:160
	global_load_dwordx2 v[40:41], v[160:161], off offset:176
	v_pk_mov_b32 v[46:47], v[38:39], v[18:19] op_sel:[1,0]
	v_mov_b32_e32 v39, v19
	v_pk_mul_f32 v[0:1], v[0:1], v[64:65] op_sel_hi:[1,0]
	v_pk_mul_f32 v[2:3], v[2:3], v[64:65] op_sel_hi:[1,0]
	v_pk_mul_f32 v[22:23], v[22:23], v[64:65] op_sel_hi:[1,0]
	v_pk_mul_f32 v[20:21], v[20:21], v[64:65] op_sel_hi:[1,0]
	v_pk_mul_f32 v[4:5], v[4:5], v[64:65] op_sel_hi:[1,0]
	v_pk_mul_f32 v[6:7], v[6:7], v[64:65] op_sel_hi:[1,0]
	v_pk_mul_f32 v[26:27], v[26:27], v[64:65] op_sel_hi:[1,0]
	v_pk_mul_f32 v[24:25], v[24:25], v[64:65] op_sel_hi:[1,0]
	v_pk_mul_f32 v[8:9], v[8:9], v[64:65] op_sel_hi:[1,0]
	v_pk_mul_f32 v[10:11], v[10:11], v[64:65] op_sel_hi:[1,0]
	s_waitcnt vmcnt(9)
	v_and_b32_e32 v44, 0xffff0000, v32
	v_lshlrev_b32_e32 v45, 16, v33
	v_lshlrev_b32_e32 v32, 16, v32
	v_and_b32_e32 v33, 0xffff0000, v33
	v_pk_add_f32 v[44:45], v[46:47], v[44:45]
	v_pk_add_f32 v[18:19], v[38:39], v[32:33]
	v_and_b32_sdwa v33, v44, v232 dst_sel:DWORD dst_unused:UNUSED_PAD src0_sel:WORD_1 src1_sel:DWORD
	v_and_b32_sdwa v38, v19, v232 dst_sel:DWORD dst_unused:UNUSED_PAD src0_sel:WORD_1 src1_sel:DWORD
	v_and_b32_sdwa v32, v45, v232 dst_sel:DWORD dst_unused:UNUSED_PAD src0_sel:WORD_1 src1_sel:DWORD
	v_add3_u32 v33, v44, v33, s81
	v_and_b32_sdwa v39, v18, v232 dst_sel:DWORD dst_unused:UNUSED_PAD src0_sel:WORD_1 src1_sel:DWORD
	v_add3_u32 v19, v19, v38, s81
	v_add3_u32 v32, v45, v32, s81
	v_and_b32_e32 v33, 0xffff0000, v33
	v_add3_u32 v18, v18, v39, s81
	v_and_b32_e32 v19, 0xffff0000, v19
	v_or_b32_sdwa v19, v19, v32 dst_sel:DWORD dst_unused:UNUSED_PAD src0_sel:DWORD src1_sel:WORD_1
	v_or_b32_sdwa v18, v18, v33 dst_sel:DWORD dst_unused:UNUSED_PAD src0_sel:WORD_1 src1_sel:DWORD
	global_load_dwordx2 v[32:33], v[160:161], off offset:224
	global_load_dwordx2 v[38:39], v[160:161], off offset:240
	v_mov_b32_e32 v47, v2
	v_mov_b32_e32 v2, v1
	v_mov_b32_e32 v46, v0
	v_pk_mul_f32 v[30:31], v[30:31], v[64:65] op_sel_hi:[1,0]
	v_pk_mul_f32 v[28:29], v[28:29], v[64:65] op_sel_hi:[1,0]
	s_waitcnt vmcnt(8)
	v_lshlrev_b32_e32 v45, 16, v35
	v_lshlrev_b32_e32 v44, 16, v34
	v_and_b32_e32 v35, 0xffff0000, v35
	v_and_b32_e32 v34, 0xffff0000, v34
	v_pk_add_f32 v[0:1], v[2:3], v[34:35]
	v_pk_add_f32 v[44:45], v[46:47], v[44:45]
	v_and_b32_sdwa v34, v1, v232 dst_sel:DWORD dst_unused:UNUSED_PAD src0_sel:WORD_1 src1_sel:DWORD
	v_and_b32_sdwa v35, v0, v232 dst_sel:DWORD dst_unused:UNUSED_PAD src0_sel:WORD_1 src1_sel:DWORD
	v_and_b32_sdwa v2, v45, v232 dst_sel:DWORD dst_unused:UNUSED_PAD src0_sel:WORD_1 src1_sel:DWORD
	v_and_b32_sdwa v3, v44, v232 dst_sel:DWORD dst_unused:UNUSED_PAD src0_sel:WORD_1 src1_sel:DWORD
	v_add3_u32 v1, v1, v34, s81
	v_add3_u32 v0, v0, v35, s81
	v_add3_u32 v3, v44, v3, s81
	v_add3_u32 v2, v45, v2, s81
	v_and_b32_e32 v1, 0xffff0000, v1
	v_and_b32_e32 v0, 0xffff0000, v0
	v_or_b32_sdwa v1, v1, v2 dst_sel:DWORD dst_unused:UNUSED_PAD src0_sel:DWORD src1_sel:WORD_1
	v_or_b32_sdwa v0, v0, v3 dst_sel:DWORD dst_unused:UNUSED_PAD src0_sel:DWORD src1_sel:WORD_1
	global_store_dwordx2 v[160:161], v[18:19], off offset:128
	global_store_dwordx2 v[160:161], v[0:1], off offset:192
	v_pk_mov_b32 v[18:19], v[20:21], v[22:23] op_sel:[1,0]
	v_mov_b32_e32 v21, v23
	v_mov_b32_e32 v23, v163
	v_mov_b32_e32 v22, v163
	s_waitcnt vmcnt(9)
	v_and_b32_e32 v0, 0xffff0000, v42
	v_lshlrev_b32_e32 v1, 16, v43
	v_lshlrev_b32_e32 v2, 16, v42
	v_and_b32_e32 v3, 0xffff0000, v43
	v_pk_add_f32 v[0:1], v[18:19], v[0:1]
	v_pk_add_f32 v[2:3], v[20:21], v[2:3]
	v_and_b32_sdwa v18, v1, v232 dst_sel:DWORD dst_unused:UNUSED_PAD src0_sel:WORD_1 src1_sel:DWORD
	v_and_b32_sdwa v19, v0, v232 dst_sel:DWORD dst_unused:UNUSED_PAD src0_sel:WORD_1 src1_sel:DWORD
	v_add3_u32 v1, v1, v18, s81
	v_and_b32_sdwa v18, v3, v232 dst_sel:DWORD dst_unused:UNUSED_PAD src0_sel:WORD_1 src1_sel:DWORD
	v_add3_u32 v0, v0, v19, s81
	v_and_b32_sdwa v19, v2, v232 dst_sel:DWORD dst_unused:UNUSED_PAD src0_sel:WORD_1 src1_sel:DWORD
	v_add3_u32 v3, v3, v18, s81
	v_and_b32_e32 v0, 0xffff0000, v0
	v_add3_u32 v2, v2, v19, s81
	v_and_b32_e32 v3, 0xffff0000, v3
	v_or_b32_sdwa v1, v3, v1 dst_sel:DWORD dst_unused:UNUSED_PAD src0_sel:DWORD src1_sel:WORD_1
	v_or_b32_sdwa v0, v2, v0 dst_sel:DWORD dst_unused:UNUSED_PAD src0_sel:WORD_1 src1_sel:DWORD
	s_waitcnt vmcnt(6)
	v_lshlrev_b32_e32 v3, 16, v37
	v_lshlrev_b32_e32 v2, 16, v36
	v_mov_b32_e32 v20, v4
	v_mov_b32_e32 v21, v6
	v_and_b32_e32 v19, 0xffff0000, v37
	v_and_b32_e32 v18, 0xffff0000, v36
	v_pk_add_f32 v[2:3], v[20:21], v[2:3]
	v_mov_b32_e32 v6, v5
	v_pk_add_f32 v[4:5], v[6:7], v[18:19]
	v_and_b32_sdwa v6, v3, v232 dst_sel:DWORD dst_unused:UNUSED_PAD src0_sel:WORD_1 src1_sel:DWORD
	v_and_b32_sdwa v7, v2, v232 dst_sel:DWORD dst_unused:UNUSED_PAD src0_sel:WORD_1 src1_sel:DWORD
	v_add3_u32 v2, v2, v7, s81
	v_add3_u32 v3, v3, v6, s81
	v_and_b32_sdwa v6, v5, v232 dst_sel:DWORD dst_unused:UNUSED_PAD src0_sel:WORD_1 src1_sel:DWORD
	v_and_b32_sdwa v7, v4, v232 dst_sel:DWORD dst_unused:UNUSED_PAD src0_sel:WORD_1 src1_sel:DWORD
	v_add3_u32 v5, v5, v6, s81
	v_add3_u32 v4, v4, v7, s81
	v_and_b32_e32 v5, 0xffff0000, v5
	v_and_b32_e32 v4, 0xffff0000, v4
	v_or_b32_sdwa v3, v5, v3 dst_sel:DWORD dst_unused:UNUSED_PAD src0_sel:DWORD src1_sel:WORD_1
	v_or_b32_sdwa v2, v4, v2 dst_sel:DWORD dst_unused:UNUSED_PAD src0_sel:DWORD src1_sel:WORD_1
	global_store_dwordx2 v[160:161], v[0:1], off offset:144
	global_store_dwordx2 v[160:161], v[2:3], off offset:208
	s_waitcnt vmcnt(7)
	v_and_b32_e32 v0, 0xffff0000, v14
	v_lshlrev_b32_e32 v1, 16, v15
	v_pk_mov_b32 v[4:5], v[24:25], v[26:27] op_sel:[1,0]
	v_lshlrev_b32_e32 v2, 16, v14
	v_and_b32_e32 v3, 0xffff0000, v15
	v_pk_add_f32 v[0:1], v[4:5], v[0:1]
	v_mov_b32_e32 v25, v27
	v_pk_add_f32 v[2:3], v[24:25], v[2:3]
	v_and_b32_sdwa v4, v1, v232 dst_sel:DWORD dst_unused:UNUSED_PAD src0_sel:WORD_1 src1_sel:DWORD
	v_and_b32_sdwa v5, v0, v232 dst_sel:DWORD dst_unused:UNUSED_PAD src0_sel:WORD_1 src1_sel:DWORD
	v_add3_u32 v1, v1, v4, s81
	v_and_b32_sdwa v4, v3, v232 dst_sel:DWORD dst_unused:UNUSED_PAD src0_sel:WORD_1 src1_sel:DWORD
	v_add3_u32 v0, v0, v5, s81
	v_and_b32_sdwa v5, v2, v232 dst_sel:DWORD dst_unused:UNUSED_PAD src0_sel:WORD_1 src1_sel:DWORD
	v_add3_u32 v3, v3, v4, s81
	v_and_b32_e32 v0, 0xffff0000, v0
	v_add3_u32 v2, v2, v5, s81
	v_and_b32_e32 v3, 0xffff0000, v3
	v_or_b32_sdwa v1, v3, v1 dst_sel:DWORD dst_unused:UNUSED_PAD src0_sel:DWORD src1_sel:WORD_1
	v_or_b32_sdwa v0, v2, v0 dst_sel:DWORD dst_unused:UNUSED_PAD src0_sel:WORD_1 src1_sel:DWORD
	s_waitcnt vmcnt(5)
	v_lshlrev_b32_e32 v3, 16, v33
	v_lshlrev_b32_e32 v2, 16, v32
	v_mov_b32_e32 v6, v8
	v_mov_b32_e32 v7, v10
	v_and_b32_e32 v5, 0xffff0000, v33
	v_and_b32_e32 v4, 0xffff0000, v32
	v_pk_add_f32 v[2:3], v[6:7], v[2:3]
	v_mov_b32_e32 v10, v9
	v_pk_add_f32 v[4:5], v[10:11], v[4:5]
	v_and_b32_sdwa v6, v3, v232 dst_sel:DWORD dst_unused:UNUSED_PAD src0_sel:WORD_1 src1_sel:DWORD
	v_and_b32_sdwa v7, v2, v232 dst_sel:DWORD dst_unused:UNUSED_PAD src0_sel:WORD_1 src1_sel:DWORD
	v_add3_u32 v2, v2, v7, s81
	v_add3_u32 v3, v3, v6, s81
	v_and_b32_sdwa v6, v5, v232 dst_sel:DWORD dst_unused:UNUSED_PAD src0_sel:WORD_1 src1_sel:DWORD
	v_and_b32_sdwa v7, v4, v232 dst_sel:DWORD dst_unused:UNUSED_PAD src0_sel:WORD_1 src1_sel:DWORD
	v_add3_u32 v5, v5, v6, s81
	v_add3_u32 v4, v4, v7, s81
	v_and_b32_e32 v5, 0xffff0000, v5
	v_and_b32_e32 v4, 0xffff0000, v4
	v_or_b32_sdwa v3, v5, v3 dst_sel:DWORD dst_unused:UNUSED_PAD src0_sel:DWORD src1_sel:WORD_1
	v_or_b32_sdwa v2, v4, v2 dst_sel:DWORD dst_unused:UNUSED_PAD src0_sel:DWORD src1_sel:WORD_1
	global_store_dwordx2 v[160:161], v[0:1], off offset:160
	global_store_dwordx2 v[160:161], v[2:3], off offset:224
	v_and_b32_e32 v0, 0xffff0000, v40
	v_lshlrev_b32_e32 v1, 16, v41
	v_pk_mov_b32 v[4:5], v[28:29], v[30:31] op_sel:[1,0]
	v_lshlrev_b32_e32 v2, 16, v40
	v_and_b32_e32 v3, 0xffff0000, v41
	v_pk_add_f32 v[0:1], v[4:5], v[0:1]
	v_mov_b32_e32 v29, v31
	v_pk_add_f32 v[2:3], v[28:29], v[2:3]
	v_and_b32_sdwa v4, v1, v232 dst_sel:DWORD dst_unused:UNUSED_PAD src0_sel:WORD_1 src1_sel:DWORD
	v_and_b32_sdwa v5, v0, v232 dst_sel:DWORD dst_unused:UNUSED_PAD src0_sel:WORD_1 src1_sel:DWORD
	v_add3_u32 v1, v1, v4, s81
	v_and_b32_sdwa v4, v3, v232 dst_sel:DWORD dst_unused:UNUSED_PAD src0_sel:WORD_1 src1_sel:DWORD
	v_add3_u32 v0, v0, v5, s81
	v_and_b32_sdwa v5, v2, v232 dst_sel:DWORD dst_unused:UNUSED_PAD src0_sel:WORD_1 src1_sel:DWORD
	v_add3_u32 v3, v3, v4, s81
	v_and_b32_e32 v0, 0xffff0000, v0
	v_add3_u32 v2, v2, v5, s81
	v_and_b32_e32 v3, 0xffff0000, v3
	v_or_b32_sdwa v1, v3, v1 dst_sel:DWORD dst_unused:UNUSED_PAD src0_sel:DWORD src1_sel:WORD_1
	v_or_b32_sdwa v0, v2, v0 dst_sel:DWORD dst_unused:UNUSED_PAD src0_sel:WORD_1 src1_sel:DWORD
	s_waitcnt vmcnt(6)
	v_lshlrev_b32_e32 v3, 16, v39
	v_lshlrev_b32_e32 v2, 16, v38
	v_mov_b32_e32 v6, v16
	v_mov_b32_e32 v7, v12
	v_and_b32_e32 v5, 0xffff0000, v39
	v_and_b32_e32 v4, 0xffff0000, v38
	v_pk_add_f32 v[2:3], v[6:7], v[2:3]
	v_mov_b32_e32 v12, v17
	v_pk_add_f32 v[4:5], v[12:13], v[4:5]
	v_and_b32_sdwa v6, v3, v232 dst_sel:DWORD dst_unused:UNUSED_PAD src0_sel:WORD_1 src1_sel:DWORD
	v_and_b32_sdwa v7, v2, v232 dst_sel:DWORD dst_unused:UNUSED_PAD src0_sel:WORD_1 src1_sel:DWORD
	v_add3_u32 v2, v2, v7, s81
	v_add3_u32 v3, v3, v6, s81
	v_and_b32_sdwa v6, v5, v232 dst_sel:DWORD dst_unused:UNUSED_PAD src0_sel:WORD_1 src1_sel:DWORD
	v_and_b32_sdwa v7, v4, v232 dst_sel:DWORD dst_unused:UNUSED_PAD src0_sel:WORD_1 src1_sel:DWORD
	v_add3_u32 v5, v5, v6, s81
	v_add3_u32 v4, v4, v7, s81
	v_and_b32_e32 v5, 0xffff0000, v5
	v_and_b32_e32 v4, 0xffff0000, v4
	v_or_b32_sdwa v3, v5, v3 dst_sel:DWORD dst_unused:UNUSED_PAD src0_sel:DWORD src1_sel:WORD_1
	v_or_b32_sdwa v2, v4, v2 dst_sel:DWORD dst_unused:UNUSED_PAD src0_sel:DWORD src1_sel:WORD_1
	global_store_dwordx2 v[160:161], v[0:1], off offset:176
	global_store_dwordx2 v[160:161], v[2:3], off offset:240
	v_mov_b32_e32 v31, v163
	v_mov_b32_e32 v30, v163
	v_mov_b32_e32 v29, v163
	v_mov_b32_e32 v28, v163
	v_mov_b32_e32 v27, v163
	v_mov_b32_e32 v26, v163
	v_mov_b32_e32 v25, v163
	v_mov_b32_e32 v24, v163
	v_mov_b32_e32 v21, v163
	v_mov_b32_e32 v20, v163
	v_mov_b32_e32 v19, v163
	v_mov_b32_e32 v18, v163
	v_mov_b32_e32 v17, v163
	v_mov_b32_e32 v16, v163
	v_mov_b32_e32 v15, v163
	v_mov_b32_e32 v14, v163
	v_mov_b32_e32 v13, v163
	v_mov_b32_e32 v12, v163
	v_mov_b32_e32 v11, v163
	v_mov_b32_e32 v10, v163
	v_mov_b32_e32 v9, v163
	v_mov_b32_e32 v8, v163
	v_mov_b32_e32 v7, v163
	v_mov_b32_e32 v6, v163
	v_mov_b32_e32 v5, v163
	v_mov_b32_e32 v4, v163
	v_mov_b32_e32 v3, v163
	v_mov_b32_e32 v2, v163
	v_mov_b32_e32 v1, v163
	v_mov_b32_e32 v0, v163
	v_mov_b32_e32 v63, v163
	v_mov_b32_e32 v62, v163
	v_mov_b32_e32 v61, v163
	v_mov_b32_e32 v60, v163
	v_mov_b32_e32 v59, v163
	v_mov_b32_e32 v58, v163
	v_mov_b32_e32 v57, v163
	v_mov_b32_e32 v56, v163
	v_mov_b32_e32 v55, v163
	v_mov_b32_e32 v54, v163
	v_mov_b32_e32 v53, v163
	v_mov_b32_e32 v52, v163
	v_mov_b32_e32 v51, v163
	v_mov_b32_e32 v50, v163
	v_mov_b32_e32 v49, v163
	v_mov_b32_e32 v48, v163
	v_mov_b32_e32 v47, v163
	v_mov_b32_e32 v46, v163
	v_mov_b32_e32 v45, v163
	v_mov_b32_e32 v44, v163
	v_mov_b32_e32 v43, v163
	v_mov_b32_e32 v42, v163
	v_mov_b32_e32 v41, v163
	v_mov_b32_e32 v40, v163
	v_mov_b32_e32 v39, v163
	v_mov_b32_e32 v38, v163
	v_mov_b32_e32 v37, v163
	v_mov_b32_e32 v36, v163
	v_mov_b32_e32 v35, v163
	v_mov_b32_e32 v34, v163
	v_mov_b32_e32 v33, v163
	v_mov_b32_e32 v32, v163
	s_cbranch_scc1 .LBB0_778
	s_lshl_b64 s[0:1], s[0:1], 1
	v_lshl_add_u64 v[210:211], v[202:203], 0, s[0:1]
	s_lshl_b32 s62, s21, 7
	v_lshl_add_u64 v[0:1], v[210:211], 0, s[62:63]
	global_load_dwordx4 v[128:131], v[0:1], off
	global_load_dwordx4 v[132:135], v[0:1], off offset:1024
	global_load_dwordx4 v[136:139], v[0:1], off offset:2048
	global_load_dwordx4 v[140:143], v[0:1], off offset:3072
	v_mov_b32_e32 v32, 0
	v_lshl_add_u64 v[212:213], v[204:205], 0, s[0:1]
	s_add_i32 s3, s3, 1
	s_lshl_b32 s12, s21, 6
	s_add_i32 s16, s91, 0xfffffe20
	v_add_u32_e32 v164, -2, v209
	v_add_u32_e32 v214, -3, v209
	v_add_u32_e32 v215, -8, v209
	v_add_u32_e32 v216, -9, v209
	v_add_u32_e32 v217, -10, v209
	v_add_u32_e32 v218, -11, v209
	v_add_u32_e32 v219, -16, v209
	v_subrev_u32_e32 v235, 17, v209
	v_subrev_u32_e32 v236, 18, v209
	v_subrev_u32_e32 v237, 19, v209
	v_subrev_u32_e32 v238, 24, v209
	v_subrev_u32_e32 v239, 25, v209
	v_subrev_u32_e32 v240, 26, v209
	v_subrev_u32_e32 v241, 27, v209
	v_mov_b32_e32 v33, v32
	v_mov_b32_e32 v34, v32
	v_mov_b32_e32 v35, v32
	v_mov_b32_e32 v36, v32
	v_mov_b32_e32 v37, v32
	v_mov_b32_e32 v38, v32
	v_mov_b32_e32 v39, v32
	v_mov_b32_e32 v40, v32
	v_mov_b32_e32 v41, v32
	v_mov_b32_e32 v42, v32
	v_mov_b32_e32 v43, v32
	v_mov_b32_e32 v44, v32
	v_mov_b32_e32 v45, v32
	v_mov_b32_e32 v46, v32
	v_mov_b32_e32 v47, v32
	v_mov_b32_e32 v48, v32
	v_mov_b32_e32 v49, v32
	v_mov_b32_e32 v50, v32
	v_mov_b32_e32 v51, v32
	v_mov_b32_e32 v52, v32
	v_mov_b32_e32 v53, v32
	v_mov_b32_e32 v54, v32
	v_mov_b32_e32 v55, v32
	v_mov_b32_e32 v56, v32
	v_mov_b32_e32 v57, v32
	v_mov_b32_e32 v58, v32
	v_mov_b32_e32 v59, v32
	v_mov_b32_e32 v60, v32
	v_mov_b32_e32 v61, v32
	v_mov_b32_e32 v62, v32
	v_mov_b32_e32 v63, v32
	v_mov_b32_e32 v0, v32
	v_mov_b32_e32 v1, v32
	v_mov_b32_e32 v2, v32
	v_mov_b32_e32 v3, v32
	v_mov_b32_e32 v4, v32
	v_mov_b32_e32 v5, v32
	v_mov_b32_e32 v6, v32
	v_mov_b32_e32 v7, v32
	v_mov_b32_e32 v8, v32
	v_mov_b32_e32 v9, v32
	v_mov_b32_e32 v10, v32
	v_mov_b32_e32 v11, v32
	v_mov_b32_e32 v12, v32
	v_mov_b32_e32 v13, v32
	v_mov_b32_e32 v14, v32
	v_mov_b32_e32 v15, v32
	v_mov_b32_e32 v16, v32
	v_mov_b32_e32 v17, v32
	v_mov_b32_e32 v18, v32
	v_mov_b32_e32 v19, v32
	v_mov_b32_e32 v20, v32
	v_mov_b32_e32 v21, v32
	v_mov_b32_e32 v22, v32
	v_mov_b32_e32 v23, v32
	v_mov_b32_e32 v24, v32
	v_mov_b32_e32 v25, v32
	v_mov_b32_e32 v26, v32
	v_mov_b32_e32 v27, v32
	v_mov_b32_e32 v28, v32
	v_mov_b32_e32 v29, v32
	v_mov_b32_e32 v30, v32
	v_mov_b32_e32 v31, v32
	v_mov_b32_e32 v162, v32
	v_mov_b32_e32 v163, v32
